# indexer head loop: removed 32 redundant self-max canonicalisations per head (relu applied in place with v_max 0,x; identical values), same packed fma accumulation
# speedup vs baseline: 1.0207x; 1.0100x over previous
.LBB0_615:
	ds_read_b128 v[18:21], v75
	ds_read_b128 v[152:155], v75 offset:32
	v_add_u32_e32 v81, s8, v132
	ds_read_b32 v156, v81
	s_add_i32 s8, s8, 4
	s_waitcnt vmcnt(7) lgkmcnt(2)
	v_mfma_f32_32x32x16_f16 v[2:17], v[34:37], v[18:21], 0
	s_cmp_lg_u32 s8, 64
	s_waitcnt vmcnt(5)
	v_mfma_f32_32x32x16_f16 v[18:33], v[42:45], v[18:21], 0
	s_waitcnt lgkmcnt(1)
	v_mfma_f32_32x32x16_f16 v[2:17], v[38:41], v[152:155], v[2:17]
	s_waitcnt vmcnt(4)
	v_mfma_f32_32x32x16_f16 v[18:33], v[46:49], v[152:155], v[18:33]
	ds_read_b128 v[152:155], v75 offset:64
	s_waitcnt vmcnt(3) lgkmcnt(0)
	v_mfma_f32_32x32x16_f16 v[2:17], v[50:53], v[152:155], v[2:17]
	s_waitcnt vmcnt(1)
	v_mfma_f32_32x32x16_f16 v[18:33], v[58:61], v[152:155], v[18:33]
	ds_read_b128 v[152:155], v75 offset:96
	v_add_u32_e32 v75, 0x80, v75
	s_waitcnt lgkmcnt(0)
	v_mfma_f32_32x32x16_f16 v[2:17], v[54:57], v[152:155], v[2:17]
	s_waitcnt vmcnt(0)
	v_mfma_f32_32x32x16_f16 v[18:33], v[62:65], v[152:155], v[18:33]
	s_nop 9
	v_max_f32_e32 v2, 0, v2
	v_max_f32_e32 v3, 0, v3
	v_max_f32_e32 v4, 0, v4
	v_max_f32_e32 v5, 0, v5
	v_max_f32_e32 v6, 0, v6
	v_max_f32_e32 v7, 0, v7
	v_max_f32_e32 v8, 0, v8
	v_max_f32_e32 v9, 0, v9
	v_max_f32_e32 v10, 0, v10
	v_max_f32_e32 v11, 0, v11
	v_max_f32_e32 v12, 0, v12
	v_max_f32_e32 v13, 0, v13
	v_max_f32_e32 v14, 0, v14
	v_max_f32_e32 v15, 0, v15
	v_max_f32_e32 v16, 0, v16
	v_max_f32_e32 v17, 0, v17
	v_max_f32_e32 v18, 0, v18
	v_max_f32_e32 v19, 0, v19
	v_max_f32_e32 v20, 0, v20
	v_max_f32_e32 v21, 0, v21
	v_max_f32_e32 v22, 0, v22
	v_max_f32_e32 v23, 0, v23
	v_max_f32_e32 v24, 0, v24
	v_max_f32_e32 v25, 0, v25
	v_max_f32_e32 v26, 0, v26
	v_max_f32_e32 v27, 0, v27
	v_max_f32_e32 v28, 0, v28
	v_max_f32_e32 v29, 0, v29
	v_max_f32_e32 v30, 0, v30
	v_max_f32_e32 v31, 0, v31
	v_max_f32_e32 v32, 0, v32
	v_max_f32_e32 v33, 0, v33
	v_pk_fma_f32 v[108:109], v[156:157], v[2:3], v[108:109] op_sel_hi:[0,1,1]
	v_pk_fma_f32 v[110:111], v[156:157], v[4:5], v[110:111] op_sel_hi:[0,1,1]
	v_pk_fma_f32 v[104:105], v[156:157], v[6:7], v[104:105] op_sel_hi:[0,1,1]
	v_pk_fma_f32 v[106:107], v[156:157], v[8:9], v[106:107] op_sel_hi:[0,1,1]
	v_pk_fma_f32 v[100:101], v[156:157], v[10:11], v[100:101] op_sel_hi:[0,1,1]
	v_pk_fma_f32 v[102:103], v[156:157], v[12:13], v[102:103] op_sel_hi:[0,1,1]
	v_pk_fma_f32 v[98:99], v[156:157], v[14:15], v[98:99] op_sel_hi:[0,1,1]
	v_pk_fma_f32 v[84:85], v[156:157], v[16:17], v[84:85] op_sel_hi:[0,1,1]
	v_pk_fma_f32 v[94:95], v[156:157], v[18:19], v[94:95] op_sel_hi:[0,1,1]
	v_pk_fma_f32 v[96:97], v[156:157], v[20:21], v[96:97] op_sel_hi:[0,1,1]
	v_pk_fma_f32 v[90:91], v[156:157], v[22:23], v[90:91] op_sel_hi:[0,1,1]
	v_pk_fma_f32 v[92:93], v[156:157], v[24:25], v[92:93] op_sel_hi:[0,1,1]
	v_pk_fma_f32 v[86:87], v[156:157], v[26:27], v[86:87] op_sel_hi:[0,1,1]
	v_pk_fma_f32 v[88:89], v[156:157], v[28:29], v[88:89] op_sel_hi:[0,1,1]
	v_pk_fma_f32 v[82:83], v[156:157], v[30:31], v[82:83] op_sel_hi:[0,1,1]
	v_pk_fma_f32 v[78:79], v[156:157], v[32:33], v[78:79] op_sel_hi:[0,1,1]
	s_cbranch_scc1 .LBB0_615
	v_ashrrev_i32_e32 v81, 31, v80
	v_lshl_add_u64 v[2:3], v[80:81], 2, v[76:77]
	v_pk_add_f32 v[4:5], v[108:109], 0 op_sel_hi:[1,0]
	v_pk_add_f32 v[6:7], v[110:111], 0 op_sel_hi:[1,0]
	global_store_dwordx4 v[2:3], v[4:7], off
	v_lshlrev_b32_e32 v8, 1, v149
	v_cmp_gt_i32_e64 s[8:9], s21, v8
	v_pk_add_f32 v[4:5], v[104:105], 0 op_sel_hi:[1,0]
	v_pk_add_f32 v[6:7], v[106:107], 0 op_sel_hi:[1,0]
	global_store_dwordx4 v[2:3], v[4:7], off offset:32
	s_nop 1
	v_pk_add_f32 v[4:5], v[100:101], 0 op_sel_hi:[1,0]
	v_pk_add_f32 v[6:7], v[102:103], 0 op_sel_hi:[1,0]
	global_store_dwordx4 v[2:3], v[4:7], off offset:64
	s_nop 1
	v_pk_add_f32 v[4:5], v[98:99], 0 op_sel_hi:[1,0]
	v_pk_add_f32 v[6:7], v[84:85], 0 op_sel_hi:[1,0]
	global_store_dwordx4 v[2:3], v[4:7], off offset:96
	s_and_saveexec_b64 s[10:11], s[8:9]
	s_cbranch_execz .LBB0_613
	v_pk_add_f32 v[4:5], v[94:95], 0 op_sel_hi:[1,0]
	v_pk_add_f32 v[6:7], v[96:97], 0 op_sel_hi:[1,0]
	global_store_dwordx4 v[2:3], v[4:7], off offset:128
	s_nop 1
	v_pk_add_f32 v[4:5], v[90:91], 0 op_sel_hi:[1,0]
	v_pk_add_f32 v[6:7], v[92:93], 0 op_sel_hi:[1,0]
	global_store_dwordx4 v[2:3], v[4:7], off offset:160
	s_nop 1
	v_pk_add_f32 v[4:5], v[86:87], 0 op_sel_hi:[1,0]
	v_pk_add_f32 v[6:7], v[88:89], 0 op_sel_hi:[1,0]
	global_store_dwordx4 v[2:3], v[4:7], off offset:192
	s_nop 1
	v_pk_add_f32 v[4:5], v[82:83], 0 op_sel_hi:[1,0]
	v_pk_add_f32 v[6:7], v[78:79], 0 op_sel_hi:[1,0]
	global_store_dwordx4 v[2:3], v[4:7], off offset:224
	s_branch .LBB0_613
